# SSD: next-next chunk dt load issued after the flag check and partner-row loads instead of before (keeps the spin wait from covering it); pre-yi vmcnt(2) dropped; on top of v61
# baseline (speedup 1.0000x reference)
.LBB0_1021:
.LBB0_1023:
	s_lshl_b32 s26, s55, 7
	s_xor_b64 s[24:25], s[90:91], -1
	s_or_b32 s27, s26, s0
	s_add_i32 s26, s26, s1
	s_cmp_lt_u32 s55, 2
	s_cselect_b32 s26, s27, s26
	v_add_u32_e32 v56, s26, v146
	v_lshl_or_b32 v164, v56, 12, v160
	v_mov_b32_e32 v63, 0
	s_andn2_b64 vcc, exec, s[24:25]
	v_mov_b32_e32 v62, 0
	v_mov_b32_e32 v61, 0
	v_mov_b32_e32 v60, 0
	v_mov_b32_e32 v59, 0
	v_mov_b32_e32 v58, 0
	v_mov_b32_e32 v57, 0
	v_mov_b32_e32 v56, 0
	s_cbranch_vccnz .LBB0_1040
	s_lshl_b32 s24, s55, 3
	s_ashr_i32 s25, s24, 31
	s_lshl_b64 s[24:25], s[24:25], 2
	s_add_u32 s90, s31, s24
	s_addc_u32 s91, s43, s25
	s_mov_b32 s83, 1
	s_branch .LBB0_1027

.LBB0_1040:
	s_cmp_lt_u32 s47, 32
	s_cselect_b64 vcc, -1, 0
	s_and_b64 vcc, s[2:3], vcc
	s_and_saveexec_b64 s[100:101], vcc
	s_cbranch_execz .Lmy_pdt_a
	s_lshl_b32 vcc_lo, s47, 7
	s_sub_i32 vcc_lo, s51, vcc_lo
	s_ashr_i32 vcc_hi, vcc_lo, 31
	v_lshl_add_u64 v[238:239], vcc, 2, v[132:133]
	global_load_dword v142, v[238:239], off
.Lmy_pdt_a:
	s_or_b64 exec, exec, s[100:101]
	s_xor_b64 s[24:25], s[22:23], -1
	s_xor_b64 s[22:23], s[78:79], -1
	s_add_i32 s47, s47, 1
	s_cmp_eq_u32 s35, 0
	s_cselect_b64 s[78:79], -1, 0
	s_andn2_b64 vcc, exec, s[24:25]
	s_mov_b64 s[24:25], -1
	s_cbranch_vccnz .LBB0_1113
	s_and_b64 s[24:25], s[78:79], exec
	s_mov_b32 s24, 0x1e400
	s_cselect_b32 s24, 0x1a000, s24
	v_add_u32_e32 v94, s24, v149
	s_nop 0
	ds_read_b128 v[66:69], v94
	ds_read_b128 v[98:101], v161
	ds_read_b128 v[70:73], v94 offset:4352
	ds_read_b128 v[74:77], v94 offset:8704
	ds_read_b128 v[82:85], v94 offset:64
	ds_read_b128 v[102:105], v161 offset:64
	s_waitcnt lgkmcnt(4)
	v_mfma_f32_16x16x32_bf16 v[66:69], v[66:69], v[98:101], 0
	ds_read_b128 v[78:81], v94 offset:13056
	s_andn2_b64 vcc, exec, s[62:63]
	s_waitcnt lgkmcnt(4)
	v_mfma_f32_16x16x32_bf16 v[70:73], v[70:73], v[98:101], 0
	s_waitcnt lgkmcnt(1)
	v_mfma_f32_16x16x32_bf16 v[66:69], v[82:85], v[102:105], v[66:69]
	ds_read_b128 v[82:85], v94 offset:4416
	v_mfma_f32_16x16x32_bf16 v[74:77], v[74:77], v[98:101], 0
	s_waitcnt lgkmcnt(0)
	v_mfma_f32_16x16x32_bf16 v[70:73], v[82:85], v[102:105], v[70:73]
	ds_read_b128 v[82:85], v94 offset:8768
	v_mfma_f32_16x16x32_bf16 v[78:81], v[78:81], v[98:101], 0
	s_waitcnt lgkmcnt(0)
	v_mfma_f32_16x16x32_bf16 v[74:77], v[82:85], v[102:105], v[74:77]
	ds_read_b128 v[82:85], v94 offset:13120
	ds_read_b128 v[86:89], v94 offset:128
	s_waitcnt lgkmcnt(1)
	v_mfma_f32_16x16x32_bf16 v[78:81], v[82:85], v[102:105], v[78:81]
	ds_read_b128 v[106:109], v161 offset:128
	ds_read_b128 v[82:85], v94 offset:4480
	s_waitcnt lgkmcnt(1)
	v_mfma_f32_16x16x32_bf16 v[66:69], v[86:89], v[106:109], v[66:69]
	ds_read_b128 v[86:89], v94 offset:8832
	s_waitcnt lgkmcnt(1)
	v_mfma_f32_16x16x32_bf16 v[70:73], v[82:85], v[106:109], v[70:73]
	ds_read_b128 v[82:85], v94 offset:13184
	s_waitcnt lgkmcnt(1)
	v_mfma_f32_16x16x32_bf16 v[74:77], v[86:89], v[106:109], v[74:77]
	ds_read_b128 v[86:89], v94 offset:192
	ds_read_b128 v[90:93], v94 offset:4544
	ds_read_b128 v[110:113], v161 offset:192
	s_waitcnt lgkmcnt(3)
	v_mfma_f32_16x16x32_bf16 v[82:85], v[82:85], v[106:109], v[78:81]
	s_waitcnt lgkmcnt(0)
	v_mfma_f32_16x16x32_bf16 v[66:69], v[86:89], v[110:113], v[66:69]
	s_nop 0
	ds_read_b128 v[78:81], v94 offset:8896
	ds_read_b128 v[86:89], v94 offset:13248
	v_mfma_f32_16x16x32_bf16 v[70:73], v[90:93], v[110:113], v[70:73]
	s_waitcnt lgkmcnt(1)
	v_mfma_f32_16x16x32_bf16 v[78:81], v[78:81], v[110:113], v[74:77]
	s_waitcnt lgkmcnt(0)
	v_mfma_f32_16x16x32_bf16 v[74:77], v[86:89], v[110:113], v[82:85]
	s_cbranch_vccnz .LBB0_1043
	s_and_b64 s[24:25], s[92:93], exec
	s_cselect_b32 s24, 1, 35
	s_sub_i32 s24, s24, s47
	s_lshl_b32 s25, s24, 7
	s_or_b32 s26, s25, s0
	s_add_i32 s25, s25, s1
	s_cmp_lt_u32 s24, 2
	s_cselect_b32 s24, s26, s25
	v_add_u32_e32 v0, s24, v137
	v_ashrrev_i32_e32 v1, 31, v0
	v_lshlrev_b64 v[0:1], 13, v[0:1]
	v_add_u32_e32 v8, s24, v138
	v_lshl_add_u64 v[0:1], s[44:45], 0, v[0:1]
	s_mov_b32 s83, s67
	v_ashrrev_i32_e32 v9, 31, v8
	v_lshl_add_u64 v[0:1], v[0:1], 0, s[82:83]
	v_lshlrev_b64 v[8:9], 13, v[8:9]
	v_add_u32_e32 v16, s24, v139
	v_lshl_add_u64 v[0:1], v[0:1], 0, v[64:65]
	s_movk_i32 s25, 0x1000
	v_lshl_add_u64 v[8:9], s[44:45], 0, v[8:9]
	v_ashrrev_i32_e32 v17, 31, v16
	v_add_co_u32_e32 v4, vcc, s25, v0
	v_lshl_add_u64 v[8:9], v[8:9], 0, s[82:83]
	v_lshlrev_b64 v[16:17], 13, v[16:17]
	v_add_u32_e32 v24, s24, v140
	v_addc_co_u32_e32 v5, vcc, 0, v1, vcc
	v_lshl_add_u64 v[8:9], v[8:9], 0, v[64:65]
	v_lshl_add_u64 v[16:17], s[44:45], 0, v[16:17]
	v_ashrrev_i32_e32 v25, 31, v24
	v_add_co_u32_e32 v12, vcc, s25, v8
	v_lshl_add_u64 v[16:17], v[16:17], 0, s[82:83]
	v_lshlrev_b64 v[24:25], 13, v[24:25]
	v_addc_co_u32_e32 v13, vcc, 0, v9, vcc
	v_lshl_add_u64 v[16:17], v[16:17], 0, v[64:65]
	v_lshl_add_u64 v[24:25], s[44:45], 0, v[24:25]
	v_add_co_u32_e32 v20, vcc, s25, v16
	v_lshl_add_u64 v[24:25], v[24:25], 0, s[82:83]
	v_add_u32_e32 v32, s24, v136
	v_addc_co_u32_e32 v21, vcc, 0, v17, vcc
	v_lshl_add_u64 v[24:25], v[24:25], 0, v[64:65]
	v_ashrrev_i32_e32 v33, 31, v32
	v_add_co_u32_e32 v28, vcc, s25, v24
	v_lshlrev_b64 v[32:33], 13, v[32:33]
	s_nop 0
	v_addc_co_u32_e32 v29, vcc, 0, v25, vcc
	v_lshl_add_u64 v[36:37], v[130:131], 0, v[32:33]
	global_load_dwordx4 v[0:3], v[4:5], off offset:2048
	s_nop 0
	global_load_dwordx4 v[4:7], v[4:5], off
	s_nop 0
	global_load_dwordx4 v[8:11], v[12:13], off offset:2048
	s_nop 0
	global_load_dwordx4 v[12:15], v[12:13], off
	s_nop 0
	global_load_dwordx4 v[16:19], v[20:21], off offset:2048
	s_nop 0
	global_load_dwordx4 v[20:23], v[20:21], off
	s_nop 0
	global_load_dwordx4 v[24:27], v[28:29], off offset:2048
	s_nop 0
	global_load_dwordx4 v[28:31], v[28:29], off
	s_nop 0
	global_load_dwordx4 v[32:35], v[36:37], off offset:16
	s_nop 0
	global_load_dwordx4 v[36:39], v[36:37], off
	s_mov_b32 s83, 0x41a00000

.LBB0_1145:
	s_xor_b64 s[24:25], s[90:91], -1
	s_and_b64 s[38:39], s[62:63], exec
	s_cselect_b32 s27, 8, 12
	s_movk_i32 s38, 0xff00
	s_cselect_b32 s38, 0x4000, s38
	s_lshl_b32 s27, s31, s27
	s_add_i32 s27, s27, s38
	s_add_i32 s27, s27, s26
	v_add_lshl_u32 v56, s27, v148, 11
	v_or3_b32 v56, v56, s43, v143
	v_lshlrev_b32_e32 v165, 1, v56
	v_mov_b32_e32 v63, 0
	s_andn2_b64 vcc, exec, s[24:25]
	v_mov_b32_e32 v62, 0
	v_mov_b32_e32 v61, 0
	v_mov_b32_e32 v60, 0
	v_mov_b32_e32 v59, 0
	v_mov_b32_e32 v58, 0
	v_mov_b32_e32 v57, 0
	v_mov_b32_e32 v56, 0
	s_cbranch_vccnz .LBB0_1162
	s_lshl_b32 s66, s34, 3
	s_lshl_b64 s[24:25], s[66:67], 2
	s_add_u32 s62, s47, s24
	s_addc_u32 s63, s51, s25
	s_mov_b32 s66, 1
	s_branch .LBB0_1149

.LBB0_1162:
	s_cmp_lt_u32 s34, 32
	s_cselect_b64 vcc, -1, 0
	s_and_b64 vcc, s[2:3], vcc
	s_and_saveexec_b64 s[100:101], vcc
	s_cbranch_execz .Lmy_pdt_b
	s_lshl_b32 vcc_lo, s34, 7
	s_or_b32 vcc_lo, vcc_lo, s69
	s_ashr_i32 vcc_hi, vcc_lo, 31
	v_lshl_add_u64 v[238:239], vcc, 2, v[134:135]
	global_load_dword v144, v[238:239], off
.Lmy_pdt_b:
	s_or_b64 exec, exec, s[100:101]
	s_xor_b64 s[24:25], s[22:23], -1
	s_xor_b64 s[36:37], s[36:37], -1
	s_add_i32 s26, s34, 1
	s_cmp_eq_u32 s83, 0
	s_cselect_b64 s[22:23], -1, 0
	s_andn2_b64 vcc, exec, s[24:25]
	s_mov_b64 s[24:25], -1
	s_cbranch_vccnz .LBB0_1235
	s_and_b64 s[24:25], s[22:23], exec
	s_mov_b32 s24, 0x1e400
	s_cselect_b32 s24, 0x1a000, s24
	v_add_u32_e32 v94, s24, v151
	s_nop 0
	ds_read_b128 v[66:69], v94
	ds_read_b128 v[102:105], v161
	ds_read_b128 v[70:73], v94 offset:4352
	ds_read_b128 v[74:77], v94 offset:8704
	ds_read_b128 v[82:85], v94 offset:64
	ds_read_b128 v[106:109], v161 offset:64
	s_waitcnt lgkmcnt(4)
	v_mfma_f32_16x16x32_bf16 v[66:69], v[66:69], v[102:105], 0
	ds_read_b128 v[78:81], v94 offset:13056
	s_andn2_b64 vcc, exec, s[20:21]
	s_waitcnt lgkmcnt(4)
	v_mfma_f32_16x16x32_bf16 v[70:73], v[70:73], v[102:105], 0
	s_waitcnt lgkmcnt(1)
	v_mfma_f32_16x16x32_bf16 v[66:69], v[82:85], v[106:109], v[66:69]
	ds_read_b128 v[82:85], v94 offset:4416
	v_mfma_f32_16x16x32_bf16 v[74:77], v[74:77], v[102:105], 0
	s_waitcnt lgkmcnt(0)
	v_mfma_f32_16x16x32_bf16 v[70:73], v[82:85], v[106:109], v[70:73]
	ds_read_b128 v[82:85], v94 offset:8768
	v_mfma_f32_16x16x32_bf16 v[78:81], v[78:81], v[102:105], 0
	s_waitcnt lgkmcnt(0)
	v_mfma_f32_16x16x32_bf16 v[74:77], v[82:85], v[106:109], v[74:77]
	ds_read_b128 v[82:85], v94 offset:13120
	ds_read_b128 v[86:89], v94 offset:128
	s_waitcnt lgkmcnt(1)
	v_mfma_f32_16x16x32_bf16 v[78:81], v[82:85], v[106:109], v[78:81]
	ds_read_b128 v[110:113], v161 offset:128
	ds_read_b128 v[82:85], v94 offset:4480
	s_waitcnt lgkmcnt(1)
	v_mfma_f32_16x16x32_bf16 v[66:69], v[86:89], v[110:113], v[66:69]
	ds_read_b128 v[86:89], v94 offset:8832
	s_waitcnt lgkmcnt(1)
	v_mfma_f32_16x16x32_bf16 v[70:73], v[82:85], v[110:113], v[70:73]
	ds_read_b128 v[82:85], v94 offset:13184
	s_waitcnt lgkmcnt(1)
	v_mfma_f32_16x16x32_bf16 v[86:89], v[86:89], v[110:113], v[74:77]
	s_nop 2
	ds_read_b128 v[74:77], v94 offset:192
	ds_read_b128 v[90:93], v94 offset:4544
	ds_read_b128 v[126:129], v161 offset:192
	s_waitcnt lgkmcnt(3)
	v_mfma_f32_16x16x32_bf16 v[82:85], v[82:85], v[110:113], v[78:81]
	s_waitcnt lgkmcnt(0)
	v_mfma_f32_16x16x32_bf16 v[78:81], v[74:77], v[126:129], v[66:69]
	s_nop 2
	ds_read_b128 v[66:69], v94 offset:8896
	v_mfma_f32_16x16x32_bf16 v[74:77], v[90:93], v[126:129], v[70:73]
	ds_read_b128 v[90:93], v94 offset:13248
	s_waitcnt lgkmcnt(1)
	v_mfma_f32_16x16x32_bf16 v[70:73], v[66:69], v[126:129], v[86:89]
	s_waitcnt lgkmcnt(0)
	v_mfma_f32_16x16x32_bf16 v[66:69], v[90:93], v[126:129], v[82:85]
	s_cbranch_vccnz .LBB0_1165
	s_lshl_b32 s24, s26, 7
	s_and_b64 s[20:21], s[56:57], exec
	s_movk_i32 s21, 0xff00
	s_cselect_b32 s20, 8, 12
	s_cselect_b32 s21, 0x4000, s21
	s_lshl_b32 s20, s31, s20
	s_add_i32 s21, s24, s21
	s_add_i32 s21, s21, s20
	v_add_u32_e32 v0, s21, v139
	v_ashrrev_i32_e32 v1, 31, v0
	v_lshlrev_b64 v[0:1], 13, v[0:1]
	v_add_u32_e32 v8, s21, v140
	v_lshl_add_u64 v[0:1], s[44:45], 0, v[0:1]
	s_mov_b32 s83, s67
	v_ashrrev_i32_e32 v9, 31, v8
	v_lshl_add_u64 v[0:1], v[0:1], 0, s[82:83]
	v_lshlrev_b64 v[8:9], 13, v[8:9]
	v_add_u32_e32 v16, s21, v141
	v_lshl_add_u64 v[0:1], v[0:1], 0, v[64:65]
	s_movk_i32 s20, 0x1000
	v_lshl_add_u64 v[8:9], s[44:45], 0, v[8:9]
	v_ashrrev_i32_e32 v17, 31, v16
	v_add_co_u32_e32 v4, vcc, s20, v0
	v_lshl_add_u64 v[8:9], v[8:9], 0, s[82:83]
	v_lshlrev_b64 v[16:17], 13, v[16:17]
	v_add_u32_e32 v24, s21, v142
	v_addc_co_u32_e32 v5, vcc, 0, v1, vcc
	v_lshl_add_u64 v[8:9], v[8:9], 0, v[64:65]
	v_lshl_add_u64 v[16:17], s[44:45], 0, v[16:17]
	v_ashrrev_i32_e32 v25, 31, v24
	v_add_co_u32_e32 v12, vcc, s20, v8
	v_lshl_add_u64 v[16:17], v[16:17], 0, s[82:83]
	v_lshlrev_b64 v[24:25], 13, v[24:25]
	v_addc_co_u32_e32 v13, vcc, 0, v9, vcc
	v_lshl_add_u64 v[16:17], v[16:17], 0, v[64:65]
	v_lshl_add_u64 v[24:25], s[44:45], 0, v[24:25]
	v_add_co_u32_e32 v20, vcc, s20, v16
	v_lshl_add_u64 v[24:25], v[24:25], 0, s[82:83]
	v_add_u32_e32 v32, s21, v138
	v_addc_co_u32_e32 v21, vcc, 0, v17, vcc
	v_lshl_add_u64 v[24:25], v[24:25], 0, v[64:65]
	v_ashrrev_i32_e32 v33, 31, v32
	v_add_co_u32_e32 v28, vcc, s20, v24
	v_lshlrev_b64 v[32:33], 13, v[32:33]
	s_nop 0
	v_addc_co_u32_e32 v29, vcc, 0, v25, vcc
	v_lshl_add_u64 v[36:37], v[132:133], 0, v[32:33]
	global_load_dwordx4 v[0:3], v[4:5], off offset:2048
	s_nop 0
	global_load_dwordx4 v[4:7], v[4:5], off
	s_nop 0
	global_load_dwordx4 v[8:11], v[12:13], off offset:2048
	s_nop 0
	global_load_dwordx4 v[12:15], v[12:13], off
	s_nop 0
	global_load_dwordx4 v[16:19], v[20:21], off offset:2048
	s_nop 0
	global_load_dwordx4 v[20:23], v[20:21], off
	s_nop 0
	global_load_dwordx4 v[24:27], v[28:29], off offset:2048
	s_nop 0
	global_load_dwordx4 v[28:31], v[28:29], off
	s_nop 0
	global_load_dwordx4 v[32:35], v[36:37], off offset:16
	s_nop 0
	global_load_dwordx4 v[36:39], v[36:37], off
